# first phase boundary: the runtime grid-sync word driven with a fan-in counter protocol (non-returning arrivals, workgroup 0 flips the generation; same end state as the runtime protocol)
# baseline (speedup 1.0000x reference)
; __global__ void __launch_bounds__(NTHR, 2) mk_fwd(Args a_by_value) {
;     ...
;         if (ph + 1 < ph_hi) cg::this_grid().sync();
.LBB0_530:
	s_waitcnt vmcnt(0) lgkmcnt(0)
	s_barrier
	s_mov_b64 s[4:5], exec
	v_readlane_b32 s6, v255, 4
	v_readlane_b32 s7, v255, 5
	s_and_b64 s[6:7], s[4:5], s[6:7]
	s_mov_b64 exec, s[6:7]
	s_cbranch_execz .LBB0_3
	s_cmp_lg_u32 s101, 0
	s_cbranch_scc1 .Lfb_fast
	s_mov_b32 s101, 1
	v_readlane_b32 s6, v255, 0
	v_readlane_b32 s7, v255, 1
	buffer_wbl2 sc1
	s_load_dwordx2 s[6:7], s[6:7], 0x58
	s_waitcnt vmcnt(0) lgkmcnt(0)
	global_load_dword v0, v1, s[6:7] offset:40
	global_load_dword v3, v1, s[6:7] offset:32 sc1
	v_mov_b32_e32 v2, 1
	s_waitcnt vmcnt(0)
	v_and_b32_e32 v3, 0xffff0000, v3
	global_atomic_add v1, v2, s[6:7] offset:32
	s_mov_b32 s13, 0x8000
	s_cmp_lg_u32 s2, 0
	s_cbranch_scc1 .Lfb1_wait
.Lfb1_master:
	global_load_dword v4, v1, s[6:7] offset:32 sc1
	s_waitcnt vmcnt(0)
	v_and_b32_e32 v4, 0xffff, v4
	v_cmp_eq_u32_e32 vcc, v4, v0
	s_cbranch_vccnz .Lfb1_flip
	s_sleep 1
	s_sub_u32 s13, s13, 1
	s_cmp_lg_u32 s13, 0
	s_cbranch_scc1 .Lfb1_master
.Lfb1_flip:
	v_sub_u32_e32 v4, 0x10000, v0
	s_nop 0
	global_atomic_add v1, v4, s[6:7] offset:32
	s_branch .LBB0_2
.Lfb1_wait:
	global_load_dword v4, v1, s[6:7] offset:32 sc1
	s_waitcnt vmcnt(0)
	v_and_b32_e32 v4, 0xffff0000, v4
	v_cmp_ne_u32_e32 vcc, v4, v3
	s_cbranch_vccnz .LBB0_2
	s_sleep 1
	s_sub_u32 s13, s13, 1
	s_cmp_lg_u32 s13, 0
	s_cbranch_scc1 .Lfb1_wait
	s_branch .LBB0_2
